# P0 p->bf16: each wave converts one contiguous 64 KiB block with a rolling 16-load pipeline (instead of 32 chunks 4 MiB apart)
# baseline (speedup 1.0000x reference)
.LBB0_22:
	v_readlane_b32 s2, v251, 40
	s_cmp_lg_u32 s2, s8
	s_mov_b64 s[8:9], -1
	s_cbranch_scc0 .LBB0_39
	s_andn2_b64 vcc, exec, s[0:1]
	s_cbranch_vccnz .LBB0_33
	s_mov_b64 s[8:9], 0
	v_mov_b64_e32 v[56:57], v[18:19]
	v_mov_b64_e32 v[58:59], v[16:17]
	v_mov_b64_e32 v[60:61], v[0:1]
	s_cmp_eq_u64 s[90:91], 0x20000
	s_cbranch_scc0 .LBB0_28
	v_readfirstlane_b32 s98, v18
	v_readfirstlane_b32 s99, v19
	v_readfirstlane_b32 s100, v16
	v_readfirstlane_b32 s101, v17
	s_nop 4
	v_subrev_u32_e32 v244, s98, v18
	v_subrev_u32_e32 v245, s100, v16
	v_readfirstlane_b32 vcc_lo, v0
	s_mul_i32 vcc_hi, vcc_lo, 0x3e0
	s_add_u32 s98, s98, vcc_hi
	s_addc_u32 s99, s99, 0
	s_mul_i32 vcc_hi, vcc_lo, 0x1f0
	s_add_u32 s100, s100, vcc_hi
	s_addc_u32 s101, s101, 0
	s_nop 4
	global_load_dwordx4 v[154:157], v244, s[98:99]
	global_load_dwordx4 v[158:161], v244, s[98:99] offset:16
	s_add_u32 s98, s98, 0x800
	s_addc_u32 s99, s99, 0
	global_load_dwordx4 v[162:165], v244, s[98:99]
	global_load_dwordx4 v[166:169], v244, s[98:99] offset:16
	s_add_u32 s98, s98, 0x800
	s_addc_u32 s99, s99, 0
	global_load_dwordx4 v[170:173], v244, s[98:99]
	global_load_dwordx4 v[174:177], v244, s[98:99] offset:16
	s_add_u32 s98, s98, 0x800
	s_addc_u32 s99, s99, 0
	global_load_dwordx4 v[178:181], v244, s[98:99]
	global_load_dwordx4 v[182:185], v244, s[98:99] offset:16
	s_add_u32 s98, s98, 0x800
	s_addc_u32 s99, s99, 0
	global_load_dwordx4 v[186:189], v244, s[98:99]
	global_load_dwordx4 v[190:193], v244, s[98:99] offset:16
	s_add_u32 s98, s98, 0x800
	s_addc_u32 s99, s99, 0
	global_load_dwordx4 v[194:197], v244, s[98:99]
	global_load_dwordx4 v[198:201], v244, s[98:99] offset:16
	s_add_u32 s98, s98, 0x800
	s_addc_u32 s99, s99, 0
	global_load_dwordx4 v[208:211], v244, s[98:99]
	global_load_dwordx4 v[212:215], v244, s[98:99] offset:16
	s_add_u32 s98, s98, 0x800
	s_addc_u32 s99, s99, 0
	global_load_dwordx4 v[228:231], v244, s[98:99]
	global_load_dwordx4 v[232:235], v244, s[98:99] offset:16
	s_add_u32 s98, s98, 0x800
	s_addc_u32 s99, s99, 0
	s_waitcnt vmcnt(14)
	v_cvt_pk_bf16_f32 v236, v154, v155
	v_cvt_pk_bf16_f32 v237, v156, v157
	v_cvt_pk_bf16_f32 v238, v158, v159
	v_cvt_pk_bf16_f32 v239, v160, v161
	global_store_dwordx4 v245, v[236:239], s[100:101]
	s_add_u32 s100, s100, 0x400
	s_addc_u32 s101, s101, 0
	global_load_dwordx4 v[154:157], v244, s[98:99]
	global_load_dwordx4 v[158:161], v244, s[98:99] offset:16
	s_add_u32 s98, s98, 0x800
	s_addc_u32 s99, s99, 0
	s_waitcnt vmcnt(15)
	v_cvt_pk_bf16_f32 v240, v162, v163
	v_cvt_pk_bf16_f32 v241, v164, v165
	v_cvt_pk_bf16_f32 v242, v166, v167
	v_cvt_pk_bf16_f32 v243, v168, v169
	global_store_dwordx4 v245, v[240:243], s[100:101]
	s_add_u32 s100, s100, 0x400
	s_addc_u32 s101, s101, 0
	global_load_dwordx4 v[162:165], v244, s[98:99]
	global_load_dwordx4 v[166:169], v244, s[98:99] offset:16
	s_add_u32 s98, s98, 0x800
	s_addc_u32 s99, s99, 0
	s_waitcnt vmcnt(16)
	v_cvt_pk_bf16_f32 v236, v170, v171
	v_cvt_pk_bf16_f32 v237, v172, v173
	v_cvt_pk_bf16_f32 v238, v174, v175
	v_cvt_pk_bf16_f32 v239, v176, v177
	global_store_dwordx4 v245, v[236:239], s[100:101]
	s_add_u32 s100, s100, 0x400
	s_addc_u32 s101, s101, 0
	global_load_dwordx4 v[170:173], v244, s[98:99]
	global_load_dwordx4 v[174:177], v244, s[98:99] offset:16
	s_add_u32 s98, s98, 0x800
	s_addc_u32 s99, s99, 0
	s_waitcnt vmcnt(17)
	v_cvt_pk_bf16_f32 v240, v178, v179
	v_cvt_pk_bf16_f32 v241, v180, v181
	v_cvt_pk_bf16_f32 v242, v182, v183
	v_cvt_pk_bf16_f32 v243, v184, v185
	global_store_dwordx4 v245, v[240:243], s[100:101]
	s_add_u32 s100, s100, 0x400
	s_addc_u32 s101, s101, 0
	global_load_dwordx4 v[178:181], v244, s[98:99]
	global_load_dwordx4 v[182:185], v244, s[98:99] offset:16
	s_add_u32 s98, s98, 0x800
	s_addc_u32 s99, s99, 0
	s_waitcnt vmcnt(18)
	v_cvt_pk_bf16_f32 v236, v186, v187
	v_cvt_pk_bf16_f32 v237, v188, v189
	v_cvt_pk_bf16_f32 v238, v190, v191
	v_cvt_pk_bf16_f32 v239, v192, v193
	global_store_dwordx4 v245, v[236:239], s[100:101]
	s_add_u32 s100, s100, 0x400
	s_addc_u32 s101, s101, 0
	global_load_dwordx4 v[186:189], v244, s[98:99]
	global_load_dwordx4 v[190:193], v244, s[98:99] offset:16
	s_add_u32 s98, s98, 0x800
	s_addc_u32 s99, s99, 0
	s_waitcnt vmcnt(19)
	v_cvt_pk_bf16_f32 v240, v194, v195
	v_cvt_pk_bf16_f32 v241, v196, v197
	v_cvt_pk_bf16_f32 v242, v198, v199
	v_cvt_pk_bf16_f32 v243, v200, v201
	global_store_dwordx4 v245, v[240:243], s[100:101]
	s_add_u32 s100, s100, 0x400
	s_addc_u32 s101, s101, 0
	global_load_dwordx4 v[194:197], v244, s[98:99]
	global_load_dwordx4 v[198:201], v244, s[98:99] offset:16
	s_add_u32 s98, s98, 0x800
	s_addc_u32 s99, s99, 0
	s_waitcnt vmcnt(20)
	v_cvt_pk_bf16_f32 v236, v208, v209
	v_cvt_pk_bf16_f32 v237, v210, v211
	v_cvt_pk_bf16_f32 v238, v212, v213
	v_cvt_pk_bf16_f32 v239, v214, v215
	global_store_dwordx4 v245, v[236:239], s[100:101]
	s_add_u32 s100, s100, 0x400
	s_addc_u32 s101, s101, 0
	global_load_dwordx4 v[208:211], v244, s[98:99]
	global_load_dwordx4 v[212:215], v244, s[98:99] offset:16
	s_add_u32 s98, s98, 0x800
	s_addc_u32 s99, s99, 0
	s_waitcnt vmcnt(21)
	v_cvt_pk_bf16_f32 v240, v228, v229
	v_cvt_pk_bf16_f32 v241, v230, v231
	v_cvt_pk_bf16_f32 v242, v232, v233
	v_cvt_pk_bf16_f32 v243, v234, v235
	global_store_dwordx4 v245, v[240:243], s[100:101]
	s_add_u32 s100, s100, 0x400
	s_addc_u32 s101, s101, 0
	global_load_dwordx4 v[228:231], v244, s[98:99]
	global_load_dwordx4 v[232:235], v244, s[98:99] offset:16
	s_add_u32 s98, s98, 0x800
	s_addc_u32 s99, s99, 0
	s_waitcnt vmcnt(21)
	v_cvt_pk_bf16_f32 v236, v154, v155
	v_cvt_pk_bf16_f32 v237, v156, v157
	v_cvt_pk_bf16_f32 v238, v158, v159
	v_cvt_pk_bf16_f32 v239, v160, v161
	global_store_dwordx4 v245, v[236:239], s[100:101]
	s_add_u32 s100, s100, 0x400
	s_addc_u32 s101, s101, 0
	global_load_dwordx4 v[154:157], v244, s[98:99]
	global_load_dwordx4 v[158:161], v244, s[98:99] offset:16
	s_add_u32 s98, s98, 0x800
	s_addc_u32 s99, s99, 0
	s_waitcnt vmcnt(21)
	v_cvt_pk_bf16_f32 v240, v162, v163
	v_cvt_pk_bf16_f32 v241, v164, v165
	v_cvt_pk_bf16_f32 v242, v166, v167
	v_cvt_pk_bf16_f32 v243, v168, v169
	global_store_dwordx4 v245, v[240:243], s[100:101]
	s_add_u32 s100, s100, 0x400
	s_addc_u32 s101, s101, 0
	global_load_dwordx4 v[162:165], v244, s[98:99]
	global_load_dwordx4 v[166:169], v244, s[98:99] offset:16
	s_add_u32 s98, s98, 0x800
	s_addc_u32 s99, s99, 0
	s_waitcnt vmcnt(21)
	v_cvt_pk_bf16_f32 v236, v170, v171
	v_cvt_pk_bf16_f32 v237, v172, v173
	v_cvt_pk_bf16_f32 v238, v174, v175
	v_cvt_pk_bf16_f32 v239, v176, v177
	global_store_dwordx4 v245, v[236:239], s[100:101]
	s_add_u32 s100, s100, 0x400
	s_addc_u32 s101, s101, 0
	global_load_dwordx4 v[170:173], v244, s[98:99]
	global_load_dwordx4 v[174:177], v244, s[98:99] offset:16
	s_add_u32 s98, s98, 0x800
	s_addc_u32 s99, s99, 0
	s_waitcnt vmcnt(21)
	v_cvt_pk_bf16_f32 v240, v178, v179
	v_cvt_pk_bf16_f32 v241, v180, v181
	v_cvt_pk_bf16_f32 v242, v182, v183
	v_cvt_pk_bf16_f32 v243, v184, v185
	global_store_dwordx4 v245, v[240:243], s[100:101]
	s_add_u32 s100, s100, 0x400
	s_addc_u32 s101, s101, 0
	global_load_dwordx4 v[178:181], v244, s[98:99]
	global_load_dwordx4 v[182:185], v244, s[98:99] offset:16
	s_add_u32 s98, s98, 0x800
	s_addc_u32 s99, s99, 0
	s_waitcnt vmcnt(21)
	v_cvt_pk_bf16_f32 v236, v186, v187
	v_cvt_pk_bf16_f32 v237, v188, v189
	v_cvt_pk_bf16_f32 v238, v190, v191
	v_cvt_pk_bf16_f32 v239, v192, v193
	global_store_dwordx4 v245, v[236:239], s[100:101]
	s_add_u32 s100, s100, 0x400
	s_addc_u32 s101, s101, 0
	global_load_dwordx4 v[186:189], v244, s[98:99]
	global_load_dwordx4 v[190:193], v244, s[98:99] offset:16
	s_add_u32 s98, s98, 0x800
	s_addc_u32 s99, s99, 0
	s_waitcnt vmcnt(21)
	v_cvt_pk_bf16_f32 v240, v194, v195
	v_cvt_pk_bf16_f32 v241, v196, v197
	v_cvt_pk_bf16_f32 v242, v198, v199
	v_cvt_pk_bf16_f32 v243, v200, v201
	global_store_dwordx4 v245, v[240:243], s[100:101]
	s_add_u32 s100, s100, 0x400
	s_addc_u32 s101, s101, 0
	global_load_dwordx4 v[194:197], v244, s[98:99]
	global_load_dwordx4 v[198:201], v244, s[98:99] offset:16
	s_add_u32 s98, s98, 0x800
	s_addc_u32 s99, s99, 0
	s_waitcnt vmcnt(21)
	v_cvt_pk_bf16_f32 v236, v208, v209
	v_cvt_pk_bf16_f32 v237, v210, v211
	v_cvt_pk_bf16_f32 v238, v212, v213
	v_cvt_pk_bf16_f32 v239, v214, v215
	global_store_dwordx4 v245, v[236:239], s[100:101]
	s_add_u32 s100, s100, 0x400
	s_addc_u32 s101, s101, 0
	global_load_dwordx4 v[208:211], v244, s[98:99]
	global_load_dwordx4 v[212:215], v244, s[98:99] offset:16
	s_add_u32 s98, s98, 0x800
	s_addc_u32 s99, s99, 0
	s_waitcnt vmcnt(21)
	v_cvt_pk_bf16_f32 v240, v228, v229
	v_cvt_pk_bf16_f32 v241, v230, v231
	v_cvt_pk_bf16_f32 v242, v232, v233
	v_cvt_pk_bf16_f32 v243, v234, v235
	global_store_dwordx4 v245, v[240:243], s[100:101]
	s_add_u32 s100, s100, 0x400
	s_addc_u32 s101, s101, 0
	global_load_dwordx4 v[228:231], v244, s[98:99]
	global_load_dwordx4 v[232:235], v244, s[98:99] offset:16
	s_add_u32 s98, s98, 0x800
	s_addc_u32 s99, s99, 0
	s_waitcnt vmcnt(21)
	v_cvt_pk_bf16_f32 v236, v154, v155
	v_cvt_pk_bf16_f32 v237, v156, v157
	v_cvt_pk_bf16_f32 v238, v158, v159
	v_cvt_pk_bf16_f32 v239, v160, v161
	global_store_dwordx4 v245, v[236:239], s[100:101]
	s_add_u32 s100, s100, 0x400
	s_addc_u32 s101, s101, 0
	global_load_dwordx4 v[154:157], v244, s[98:99]
	global_load_dwordx4 v[158:161], v244, s[98:99] offset:16
	s_add_u32 s98, s98, 0x800
	s_addc_u32 s99, s99, 0
	s_waitcnt vmcnt(21)
	v_cvt_pk_bf16_f32 v240, v162, v163
	v_cvt_pk_bf16_f32 v241, v164, v165
	v_cvt_pk_bf16_f32 v242, v166, v167
	v_cvt_pk_bf16_f32 v243, v168, v169
	global_store_dwordx4 v245, v[240:243], s[100:101]
	s_add_u32 s100, s100, 0x400
	s_addc_u32 s101, s101, 0
	global_load_dwordx4 v[162:165], v244, s[98:99]
	global_load_dwordx4 v[166:169], v244, s[98:99] offset:16
	s_add_u32 s98, s98, 0x800
	s_addc_u32 s99, s99, 0
	s_waitcnt vmcnt(21)
	v_cvt_pk_bf16_f32 v236, v170, v171
	v_cvt_pk_bf16_f32 v237, v172, v173
	v_cvt_pk_bf16_f32 v238, v174, v175
	v_cvt_pk_bf16_f32 v239, v176, v177
	global_store_dwordx4 v245, v[236:239], s[100:101]
	s_add_u32 s100, s100, 0x400
	s_addc_u32 s101, s101, 0
	global_load_dwordx4 v[170:173], v244, s[98:99]
	global_load_dwordx4 v[174:177], v244, s[98:99] offset:16
	s_add_u32 s98, s98, 0x800
	s_addc_u32 s99, s99, 0
	s_waitcnt vmcnt(21)
	v_cvt_pk_bf16_f32 v240, v178, v179
	v_cvt_pk_bf16_f32 v241, v180, v181
	v_cvt_pk_bf16_f32 v242, v182, v183
	v_cvt_pk_bf16_f32 v243, v184, v185
	global_store_dwordx4 v245, v[240:243], s[100:101]
	s_add_u32 s100, s100, 0x400
	s_addc_u32 s101, s101, 0
	global_load_dwordx4 v[178:181], v244, s[98:99]
	global_load_dwordx4 v[182:185], v244, s[98:99] offset:16
	s_add_u32 s98, s98, 0x800
	s_addc_u32 s99, s99, 0
	s_waitcnt vmcnt(21)
	v_cvt_pk_bf16_f32 v236, v186, v187
	v_cvt_pk_bf16_f32 v237, v188, v189
	v_cvt_pk_bf16_f32 v238, v190, v191
	v_cvt_pk_bf16_f32 v239, v192, v193
	global_store_dwordx4 v245, v[236:239], s[100:101]
	s_add_u32 s100, s100, 0x400
	s_addc_u32 s101, s101, 0
	global_load_dwordx4 v[186:189], v244, s[98:99]
	global_load_dwordx4 v[190:193], v244, s[98:99] offset:16
	s_add_u32 s98, s98, 0x800
	s_addc_u32 s99, s99, 0
	s_waitcnt vmcnt(21)
	v_cvt_pk_bf16_f32 v240, v194, v195
	v_cvt_pk_bf16_f32 v241, v196, v197
	v_cvt_pk_bf16_f32 v242, v198, v199
	v_cvt_pk_bf16_f32 v243, v200, v201
	global_store_dwordx4 v245, v[240:243], s[100:101]
	s_add_u32 s100, s100, 0x400
	s_addc_u32 s101, s101, 0
	global_load_dwordx4 v[194:197], v244, s[98:99]
	global_load_dwordx4 v[198:201], v244, s[98:99] offset:16
	s_add_u32 s98, s98, 0x800
	s_addc_u32 s99, s99, 0
	s_waitcnt vmcnt(21)
	v_cvt_pk_bf16_f32 v236, v208, v209
	v_cvt_pk_bf16_f32 v237, v210, v211
	v_cvt_pk_bf16_f32 v238, v212, v213
	v_cvt_pk_bf16_f32 v239, v214, v215
	global_store_dwordx4 v245, v[236:239], s[100:101]
	s_add_u32 s100, s100, 0x400
	s_addc_u32 s101, s101, 0
	global_load_dwordx4 v[208:211], v244, s[98:99]
	global_load_dwordx4 v[212:215], v244, s[98:99] offset:16
	s_add_u32 s98, s98, 0x800
	s_addc_u32 s99, s99, 0
	s_waitcnt vmcnt(21)
	v_cvt_pk_bf16_f32 v240, v228, v229
	v_cvt_pk_bf16_f32 v241, v230, v231
	v_cvt_pk_bf16_f32 v242, v232, v233
	v_cvt_pk_bf16_f32 v243, v234, v235
	global_store_dwordx4 v245, v[240:243], s[100:101]
	s_add_u32 s100, s100, 0x400
	s_addc_u32 s101, s101, 0
	global_load_dwordx4 v[228:231], v244, s[98:99]
	global_load_dwordx4 v[232:235], v244, s[98:99] offset:16
	s_add_u32 s98, s98, 0x800
	s_addc_u32 s99, s99, 0
	s_waitcnt vmcnt(21)
	v_cvt_pk_bf16_f32 v236, v154, v155
	v_cvt_pk_bf16_f32 v237, v156, v157
	v_cvt_pk_bf16_f32 v238, v158, v159
	v_cvt_pk_bf16_f32 v239, v160, v161
	global_store_dwordx4 v245, v[236:239], s[100:101]
	s_add_u32 s100, s100, 0x400
	s_addc_u32 s101, s101, 0
	s_waitcnt vmcnt(19)
	v_cvt_pk_bf16_f32 v240, v162, v163
	v_cvt_pk_bf16_f32 v241, v164, v165
	v_cvt_pk_bf16_f32 v242, v166, v167
	v_cvt_pk_bf16_f32 v243, v168, v169
	global_store_dwordx4 v245, v[240:243], s[100:101]
	s_add_u32 s100, s100, 0x400
	s_addc_u32 s101, s101, 0
	s_waitcnt vmcnt(17)
	v_cvt_pk_bf16_f32 v236, v170, v171
	v_cvt_pk_bf16_f32 v237, v172, v173
	v_cvt_pk_bf16_f32 v238, v174, v175
	v_cvt_pk_bf16_f32 v239, v176, v177
	global_store_dwordx4 v245, v[236:239], s[100:101]
	s_add_u32 s100, s100, 0x400
	s_addc_u32 s101, s101, 0
	s_waitcnt vmcnt(15)
	v_cvt_pk_bf16_f32 v240, v178, v179
	v_cvt_pk_bf16_f32 v241, v180, v181
	v_cvt_pk_bf16_f32 v242, v182, v183
	v_cvt_pk_bf16_f32 v243, v184, v185
	global_store_dwordx4 v245, v[240:243], s[100:101]
	s_add_u32 s100, s100, 0x400
	s_addc_u32 s101, s101, 0
	s_waitcnt vmcnt(13)
	v_cvt_pk_bf16_f32 v236, v186, v187
	v_cvt_pk_bf16_f32 v237, v188, v189
	v_cvt_pk_bf16_f32 v238, v190, v191
	v_cvt_pk_bf16_f32 v239, v192, v193
	global_store_dwordx4 v245, v[236:239], s[100:101]
	s_add_u32 s100, s100, 0x400
	s_addc_u32 s101, s101, 0
	s_waitcnt vmcnt(11)
	v_cvt_pk_bf16_f32 v240, v194, v195
	v_cvt_pk_bf16_f32 v241, v196, v197
	v_cvt_pk_bf16_f32 v242, v198, v199
	v_cvt_pk_bf16_f32 v243, v200, v201
	global_store_dwordx4 v245, v[240:243], s[100:101]
	s_add_u32 s100, s100, 0x400
	s_addc_u32 s101, s101, 0
	s_waitcnt vmcnt(9)
	v_cvt_pk_bf16_f32 v236, v208, v209
	v_cvt_pk_bf16_f32 v237, v210, v211
	v_cvt_pk_bf16_f32 v238, v212, v213
	v_cvt_pk_bf16_f32 v239, v214, v215
	global_store_dwordx4 v245, v[236:239], s[100:101]
	s_add_u32 s100, s100, 0x400
	s_addc_u32 s101, s101, 0
	s_waitcnt vmcnt(7)
	v_cvt_pk_bf16_f32 v240, v228, v229
	v_cvt_pk_bf16_f32 v241, v230, v231
	v_cvt_pk_bf16_f32 v242, v232, v233
	v_cvt_pk_bf16_f32 v243, v234, v235
	global_store_dwordx4 v245, v[240:243], s[100:101]
	s_add_u32 s100, s100, 0x400
	s_addc_u32 s101, s101, 0
	s_branch .LBB0_33
	s_branch .LBB0_28
